# v21 plus grid barrier with one fewer hop: the last arriving XCD leader bumps every XCD generation word directly instead of a top generation word that the other leaders poll and re-broadcast
# baseline (speedup 1.0000x reference)
; __device__ __forceinline__ unsigned xb_add(unsigned* p, unsigned v) { return __hip_atomic_fetch_add(p, v, __ATOMIC_RELAXED, __HIP_MEMORY_SCOPE_AGENT); }
; __device__ __forceinline__ void xcd_barrier(const XcdBarrier& b) {
;     ...
;             __builtin_amdgcn_fence(__ATOMIC_ACQUIRE, "agent");
;             xb_add(&bar[XB_XGEN(b.x)], 1u);
;             asm volatile("s_waitcnt vmcnt(0)" ::: "memory");
.LBB0_12:
	s_or_b64 exec, exec, s[4:5]
	s_waitcnt vmcnt(0)
	buffer_inv sc1
	s_waitcnt vmcnt(0)

; __device__ __forceinline__ unsigned xb_ld(unsigned* p)              { return __hip_atomic_load(p, __ATOMIC_RELAXED, __HIP_MEMORY_SCOPE_AGENT); }
; __device__ __forceinline__ unsigned xb_add(unsigned* p, unsigned v) { return __hip_atomic_fetch_add(p, v, __ATOMIC_RELAXED, __HIP_MEMORY_SCOPE_AGENT); }
; #define XB_SPIN(cond, bar) do { unsigned _sp = 0; while (cond) { __builtin_amdgcn_s_sleep(1); \
;     if ((++_sp & 255u) == 0u) { if (xb_ld(&(bar)[XB_TMO])) break; if (_sp > XB_SPIN_CAP) { atomicAdd(&(bar)[XB_TMO], 1u); break; } } } } while (0)
; __device__ __forceinline__ void xcd_barrier(const XcdBarrier& b) {
;     ...
;     if (threadIdx.x == 0) {
;         unsigned* bar = b.bar;
;         __builtin_amdgcn_s_waitcnt(0);
;         unsigned nloc = b.st[0], nx = b.st[1];
;         if (nloc == 0u) { xcd_barrier_complete(bar, b.x, nloc, nx); b.st[0] = nloc; b.st[1] = nx; }
;         const unsigned old = xb_add(&bar[XB_XSUB(b.x)], 1u);
;         const unsigned gen = old / nloc;
;         if (old + 1u == (gen + 1u) * nloc) {
;             __builtin_amdgcn_fence(__ATOMIC_RELEASE, "agent");
;             asm volatile("s_waitcnt vmcnt(0)" ::: "memory");
;             const unsigned og = xb_add(&bar[XB_TOP], 1u);
;             const unsigned tg = og / nx;
;             if (og + 1u == (tg + 1u) * nx) xb_add(&bar[XB_TOPGEN], 1u);
;             else XB_SPIN(xb_ld(&bar[XB_TOPGEN]) == tg, bar);
;             __builtin_amdgcn_fence(__ATOMIC_ACQUIRE, "agent");
;             xb_add(&bar[XB_XGEN(b.x)], 1u);
;             asm volatile("s_waitcnt vmcnt(0)" ::: "memory");
;         } else {
;             XB_SPIN(xb_ld(&bar[XB_XGEN(b.x)]) == gen, bar);
.LBB0_95:
	v_readlane_b32 s2, v254, 56
	s_lshl_b32 s86, s2, 6
	s_lshl_b64 s[2:3], s[86:87], 2
	s_add_u32 s2, s90, s2
	s_addc_u32 s3, s91, s3
	v_cvt_f32_u32_e32 v2, v3
	global_atomic_add v4, v224, v197, s[2:3] offset:1024 sc0
	v_sub_u32_e32 v5, 0, v3
	v_rcp_iflag_f32_e32 v2, v2
	s_nop 0
	v_mul_f32_e32 v2, 0x4f7ffffe, v2
	v_cvt_u32_f32_e32 v2, v2
	v_mul_lo_u32 v5, v5, v2
	v_mul_hi_u32 v5, v2, v5
	v_add_u32_e32 v2, v2, v5
	s_waitcnt vmcnt(0)
	v_mul_hi_u32 v2, v4, v2
	v_mul_lo_u32 v5, v2, v3
	v_sub_u32_e32 v5, v4, v5
	v_add_u32_e32 v6, 1, v2
	v_cmp_ge_u32_e32 vcc, v5, v3
	v_add_u32_e32 v4, 1, v4
	s_nop 0
	v_cndmask_b32_e32 v2, v2, v6, vcc
	v_sub_u32_e32 v6, v5, v3
	v_cndmask_b32_e32 v5, v5, v6, vcc
	v_add_u32_e32 v6, 1, v2
	v_cmp_ge_u32_e32 vcc, v5, v3
	s_nop 1
	v_cndmask_b32_e32 v2, v2, v6, vcc
	v_mul_lo_u32 v5, v3, v2
	v_add_u32_e32 v3, v5, v3
	v_cmp_ne_u32_e32 vcc, v4, v3
	v_mov_b32_e32 v246, v2
	s_and_saveexec_b64 s[4:5], vcc
	s_xor_b64 s[4:5], exec, s[4:5]
	s_cbranch_execz .LBB0_108
	s_waitcnt lgkmcnt(0)
	global_load_dword v0, v225, s[2:3] offset:1024 sc1
	s_add_u32 s8, s2, 0x2400
	s_addc_u32 s9, s3, 0
	s_waitcnt vmcnt(0)
	v_cmp_eq_u32_e32 vcc, v0, v2
	s_and_saveexec_b64 s[6:7], vcc
	s_cbranch_execz .LBB0_107
	s_mov_b32 s20, 1
	s_mov_b64 s[10:11], 0
	s_branch .LBB0_99

; __device__ __forceinline__ unsigned xb_ld(unsigned* p)              { return __hip_atomic_load(p, __ATOMIC_RELAXED, __HIP_MEMORY_SCOPE_AGENT); }
; __device__ __forceinline__ unsigned xb_add(unsigned* p, unsigned v) { return __hip_atomic_fetch_add(p, v, __ATOMIC_RELAXED, __HIP_MEMORY_SCOPE_AGENT); }
; #define XB_SPIN(cond, bar) do { unsigned _sp = 0; while (cond) { __builtin_amdgcn_s_sleep(1); \
;     if ((++_sp & 255u) == 0u) { if (xb_ld(&(bar)[XB_TMO])) break; if (_sp > XB_SPIN_CAP) { atomicAdd(&(bar)[XB_TMO], 1u); break; } } } } while (0)
; __device__ __forceinline__ void xcd_barrier(const XcdBarrier& b) {
;     ...
;         if (old + 1u == (gen + 1u) * nloc) {
;             __builtin_amdgcn_fence(__ATOMIC_RELEASE, "agent");
;             asm volatile("s_waitcnt vmcnt(0)" ::: "memory");
;             const unsigned og = xb_add(&bar[XB_TOP], 1u);
;             const unsigned tg = og / nx;
;             if (og + 1u == (tg + 1u) * nx) xb_add(&bar[XB_TOPGEN], 1u);
;             else XB_SPIN(xb_ld(&bar[XB_TOPGEN]) == tg, bar);
.LBB0_108:
	s_andn2_saveexec_b64 s[4:5], s[4:5]
	s_cbranch_execz .LBB0_124
	buffer_wbl2 sc1
	s_waitcnt lgkmcnt(0)
	s_waitcnt vmcnt(0)
	global_atomic_add v2, v226, v197, s[90:91] offset:1024 sc0
	v_cvt_f32_u32_e32 v3, v0
	v_sub_u32_e32 v4, 0, v0
	s_add_u32 s4, s2, 0x2400
	s_addc_u32 s5, s3, 0
	v_rcp_iflag_f32_e32 v3, v3
	s_mov_b64 s[8:9], -1
	v_mul_f32_e32 v3, 0x4f7ffffe, v3
	v_cvt_u32_f32_e32 v3, v3
	v_mul_lo_u32 v4, v4, v3
	v_mul_hi_u32 v4, v3, v4
	v_add_u32_e32 v3, v3, v4
	s_waitcnt vmcnt(0)
	v_mul_hi_u32 v3, v2, v3
	v_mul_lo_u32 v4, v3, v0
	v_add_u32_e32 v5, 1, v2
	v_sub_u32_e32 v2, v2, v4
	v_add_u32_e32 v6, 1, v3
	v_cmp_ge_u32_e32 vcc, v2, v0
	v_sub_u32_e32 v4, v2, v0
	s_nop 0
	v_cndmask_b32_e32 v3, v3, v6, vcc
	v_cndmask_b32_e32 v2, v2, v4, vcc
	v_add_u32_e32 v4, 1, v3
	v_cmp_ge_u32_e32 vcc, v2, v0
	s_nop 1
	v_cndmask_b32_e32 v4, v3, v4, vcc
	v_mul_lo_u32 v2, v0, v4
	v_add_u32_e32 v0, v2, v0
	v_cmp_ne_u32_e32 vcc, v5, v0
	v_mov_b64_e32 v[2:3], s[4:5]
	s_and_saveexec_b64 s[6:7], vcc
	s_cbranch_execz .LBB0_121
	global_load_dword v0, v1, s[4:5] sc1
	s_mov_b64 s[12:13], 0
	s_waitcnt vmcnt(0)
	v_cmp_eq_u32_e32 vcc, v0, v246
	s_and_saveexec_b64 s[10:11], vcc
	s_cbranch_execz .LBB0_120
	s_add_u32 s8, s90, 0x200
	s_addc_u32 s9, s91, 0
	s_mov_b32 s22, 1
	s_branch .LBB0_113

; __device__ __forceinline__ unsigned xb_ld(unsigned* p)              { return __hip_atomic_load(p, __ATOMIC_RELAXED, __HIP_MEMORY_SCOPE_AGENT); }
; #define XB_SPIN(cond, bar) do { unsigned _sp = 0; while (cond) { __builtin_amdgcn_s_sleep(1); \
;     if ((++_sp & 255u) == 0u) { if (xb_ld(&(bar)[XB_TMO])) break; if (_sp > XB_SPIN_CAP) { atomicAdd(&(bar)[XB_TMO], 1u); break; } } } } while (0)
; __device__ __forceinline__ void xcd_barrier(const XcdBarrier& b) {
;     ...
;             else XB_SPIN(xb_ld(&bar[XB_TOPGEN]) == tg, bar);
.LBB0_115:
	global_load_dword v0, v1, s[4:5] sc1
	s_add_i32 s22, s22, 1
	s_mov_b64 s[18:19], -1
	s_waitcnt vmcnt(0)
	v_cmp_ne_u32_e32 vcc, v0, v246
	s_orn2_b64 s[16:17], vcc, exec
	s_branch .LBB0_112

; __device__ __forceinline__ unsigned xb_add(unsigned* p, unsigned v) { return __hip_atomic_fetch_add(p, v, __ATOMIC_RELAXED, __HIP_MEMORY_SCOPE_AGENT); }
; __device__ __forceinline__ void xcd_barrier(const XcdBarrier& b) {
;     ...
;             if (og + 1u == (tg + 1u) * nx) xb_add(&bar[XB_TOPGEN], 1u);
.LBB0_121:
	s_or_b64 exec, exec, s[6:7]
	s_and_saveexec_b64 s[4:5], s[8:9]
	s_cbranch_execz .LBB0_123
	global_atomic_add v225, v197, s[90:91] offset:1024
	global_atomic_add v225, v197, s[90:91] offset:1280
	global_atomic_add v225, v197, s[90:91] offset:1536
	global_atomic_add v225, v197, s[90:91] offset:1792
	global_atomic_add v225, v197, s[90:91] offset:2048
	global_atomic_add v225, v197, s[90:91] offset:2304
	global_atomic_add v225, v197, s[90:91] offset:2560
	global_atomic_add v225, v197, s[90:91] offset:2816
	global_atomic_add v225, v197, s[90:91] offset:3072
	global_atomic_add v225, v197, s[90:91] offset:3328
	global_atomic_add v225, v197, s[90:91] offset:3584
	global_atomic_add v225, v197, s[90:91] offset:3840
	global_atomic_add v226, v197, s[90:91]
	global_atomic_add v226, v197, s[90:91] offset:256
	global_atomic_add v226, v197, s[90:91] offset:512
	global_atomic_add v226, v197, s[90:91] offset:768

; __device__ __forceinline__ unsigned xb_ld(unsigned* p)              { return __hip_atomic_load(p, __ATOMIC_RELAXED, __HIP_MEMORY_SCOPE_AGENT); }
; __device__ __forceinline__ unsigned xb_add(unsigned* p, unsigned v) { return __hip_atomic_fetch_add(p, v, __ATOMIC_RELAXED, __HIP_MEMORY_SCOPE_AGENT); }
; #define XB_SPIN(cond, bar) do { unsigned _sp = 0; while (cond) { __builtin_amdgcn_s_sleep(1); \
;     if ((++_sp & 255u) == 0u) { if (xb_ld(&(bar)[XB_TMO])) break; if (_sp > XB_SPIN_CAP) { atomicAdd(&(bar)[XB_TMO], 1u); break; } } } } while (0)
; __device__ __forceinline__ void xcd_barrier(const XcdBarrier& b) {
;     ...
;     if (threadIdx.x == 0) {
;         unsigned* bar = b.bar;
;         __builtin_amdgcn_s_waitcnt(0);
;         unsigned nloc = b.st[0], nx = b.st[1];
;         if (nloc == 0u) { xcd_barrier_complete(bar, b.x, nloc, nx); b.st[0] = nloc; b.st[1] = nx; }
;         const unsigned old = xb_add(&bar[XB_XSUB(b.x)], 1u);
;         const unsigned gen = old / nloc;
;         if (old + 1u == (gen + 1u) * nloc) {
;             __builtin_amdgcn_fence(__ATOMIC_RELEASE, "agent");
;             asm volatile("s_waitcnt vmcnt(0)" ::: "memory");
;             const unsigned og = xb_add(&bar[XB_TOP], 1u);
;             const unsigned tg = og / nx;
;             if (og + 1u == (tg + 1u) * nx) xb_add(&bar[XB_TOPGEN], 1u);
;             else XB_SPIN(xb_ld(&bar[XB_TOPGEN]) == tg, bar);
;             __builtin_amdgcn_fence(__ATOMIC_ACQUIRE, "agent");
;             xb_add(&bar[XB_XGEN(b.x)], 1u);
;             asm volatile("s_waitcnt vmcnt(0)" ::: "memory");
;         } else {
;             XB_SPIN(xb_ld(&bar[XB_XGEN(b.x)]) == gen, bar);
.LBB0_254:
	v_readlane_b32 s2, v254, 56
	s_lshl_b32 s86, s2, 6
	s_lshl_b64 s[2:3], s[86:87], 2
	s_add_u32 s2, s90, s2
	s_addc_u32 s3, s91, s3
	v_cvt_f32_u32_e32 v0, v3
	global_atomic_add v4, v224, v197, s[2:3] offset:1024 sc0
	v_sub_u32_e32 v5, 0, v3
	v_rcp_iflag_f32_e32 v0, v0
	s_nop 0
	v_mul_f32_e32 v0, 0x4f7ffffe, v0
	v_cvt_u32_f32_e32 v0, v0
	v_mul_lo_u32 v5, v5, v0
	v_mul_hi_u32 v5, v0, v5
	v_add_u32_e32 v0, v0, v5
	s_waitcnt vmcnt(0)
	v_mul_hi_u32 v0, v4, v0
	v_mul_lo_u32 v5, v0, v3
	v_sub_u32_e32 v5, v4, v5
	v_add_u32_e32 v6, 1, v0
	v_cmp_ge_u32_e32 vcc, v5, v3
	v_add_u32_e32 v4, 1, v4
	s_nop 0
	v_cndmask_b32_e32 v0, v0, v6, vcc
	v_sub_u32_e32 v6, v5, v3
	v_cndmask_b32_e32 v5, v5, v6, vcc
	v_add_u32_e32 v6, 1, v0
	v_cmp_ge_u32_e32 vcc, v5, v3
	s_nop 1
	v_cndmask_b32_e32 v0, v0, v6, vcc
	v_mul_lo_u32 v5, v3, v0
	v_add_u32_e32 v3, v5, v3
	v_cmp_ne_u32_e32 vcc, v4, v3
	v_mov_b32_e32 v246, v0
	s_and_saveexec_b64 s[4:5], vcc
	s_xor_b64 s[4:5], exec, s[4:5]
	s_cbranch_execz .LBB0_267
	s_waitcnt lgkmcnt(0)
	global_load_dword v2, v225, s[2:3] offset:1024 sc1
	s_add_u32 s8, s2, 0x2400
	s_addc_u32 s9, s3, 0
	s_waitcnt vmcnt(0)
	v_cmp_eq_u32_e32 vcc, v2, v0
	s_and_saveexec_b64 s[6:7], vcc
	s_cbranch_execz .LBB0_266
	s_mov_b32 s20, 1
	s_mov_b64 s[10:11], 0
	s_branch .LBB0_258

; __device__ __forceinline__ unsigned xb_ld(unsigned* p)              { return __hip_atomic_load(p, __ATOMIC_RELAXED, __HIP_MEMORY_SCOPE_AGENT); }
; __device__ __forceinline__ unsigned xb_add(unsigned* p, unsigned v) { return __hip_atomic_fetch_add(p, v, __ATOMIC_RELAXED, __HIP_MEMORY_SCOPE_AGENT); }
; #define XB_SPIN(cond, bar) do { unsigned _sp = 0; while (cond) { __builtin_amdgcn_s_sleep(1); \
;     if ((++_sp & 255u) == 0u) { if (xb_ld(&(bar)[XB_TMO])) break; if (_sp > XB_SPIN_CAP) { atomicAdd(&(bar)[XB_TMO], 1u); break; } } } } while (0)
; __device__ __forceinline__ void xcd_barrier(const XcdBarrier& b) {
;     ...
;         if (old + 1u == (gen + 1u) * nloc) {
;             __builtin_amdgcn_fence(__ATOMIC_RELEASE, "agent");
;             asm volatile("s_waitcnt vmcnt(0)" ::: "memory");
;             const unsigned og = xb_add(&bar[XB_TOP], 1u);
;             const unsigned tg = og / nx;
;             if (og + 1u == (tg + 1u) * nx) xb_add(&bar[XB_TOPGEN], 1u);
;             else XB_SPIN(xb_ld(&bar[XB_TOPGEN]) == tg, bar);
.LBB0_267:
	s_andn2_saveexec_b64 s[4:5], s[4:5]
	s_cbranch_execz .LBB0_283
	buffer_wbl2 sc1
	s_waitcnt lgkmcnt(0)
	s_waitcnt vmcnt(0)
	global_atomic_add v3, v226, v197, s[90:91] offset:1024 sc0
	v_cvt_f32_u32_e32 v0, v2
	v_sub_u32_e32 v4, 0, v2
	s_add_u32 s4, s2, 0x2400
	s_addc_u32 s5, s3, 0
	v_rcp_iflag_f32_e32 v0, v0
	s_mov_b64 s[8:9], -1
	v_mul_f32_e32 v0, 0x4f7ffffe, v0
	v_cvt_u32_f32_e32 v0, v0
	v_mul_lo_u32 v4, v4, v0
	v_mul_hi_u32 v4, v0, v4
	v_add_u32_e32 v0, v0, v4
	s_waitcnt vmcnt(0)
	v_mul_hi_u32 v0, v3, v0
	v_mul_lo_u32 v4, v0, v2
	v_sub_u32_e32 v4, v3, v4
	v_cmp_ge_u32_e32 vcc, v4, v2
	v_add_u32_e32 v5, 1, v0
	v_add_u32_e32 v3, 1, v3
	v_cndmask_b32_e32 v0, v0, v5, vcc
	v_sub_u32_e32 v5, v4, v2
	v_cndmask_b32_e32 v4, v4, v5, vcc
	v_cmp_ge_u32_e32 vcc, v4, v2
	v_add_u32_e32 v4, 1, v0
	s_nop 0
	v_cndmask_b32_e32 v0, v0, v4, vcc
	v_mul_lo_u32 v4, v2, v0
	v_add_u32_e32 v2, v4, v2
	v_cmp_ne_u32_e32 vcc, v3, v2
	v_mov_b64_e32 v[2:3], s[4:5]
	s_and_saveexec_b64 s[6:7], vcc
	s_cbranch_execz .LBB0_280
	global_load_dword v2, v1, s[4:5] sc1
	s_mov_b64 s[12:13], 0
	s_waitcnt vmcnt(0)
	v_cmp_eq_u32_e32 vcc, v2, v246
	s_and_saveexec_b64 s[10:11], vcc
	s_cbranch_execz .LBB0_279
	s_add_u32 s8, s90, 0x200
	s_addc_u32 s9, s91, 0
	s_mov_b32 s22, 1
	s_branch .LBB0_272

; __device__ __forceinline__ unsigned xb_ld(unsigned* p)              { return __hip_atomic_load(p, __ATOMIC_RELAXED, __HIP_MEMORY_SCOPE_AGENT); }
; #define XB_SPIN(cond, bar) do { unsigned _sp = 0; while (cond) { __builtin_amdgcn_s_sleep(1); \
;     if ((++_sp & 255u) == 0u) { if (xb_ld(&(bar)[XB_TMO])) break; if (_sp > XB_SPIN_CAP) { atomicAdd(&(bar)[XB_TMO], 1u); break; } } } } while (0)
; __device__ __forceinline__ void xcd_barrier(const XcdBarrier& b) {
;     ...
;             else XB_SPIN(xb_ld(&bar[XB_TOPGEN]) == tg, bar);
.LBB0_274:
	global_load_dword v2, v1, s[4:5] sc1
	s_add_i32 s22, s22, 1
	s_mov_b64 s[18:19], -1
	s_waitcnt vmcnt(0)
	v_cmp_ne_u32_e32 vcc, v2, v246
	s_orn2_b64 s[16:17], vcc, exec
	s_branch .LBB0_271

; __device__ __forceinline__ unsigned xb_ld(unsigned* p)              { return __hip_atomic_load(p, __ATOMIC_RELAXED, __HIP_MEMORY_SCOPE_AGENT); }
; __device__ __forceinline__ unsigned xb_add(unsigned* p, unsigned v) { return __hip_atomic_fetch_add(p, v, __ATOMIC_RELAXED, __HIP_MEMORY_SCOPE_AGENT); }
; #define XB_SPIN(cond, bar) do { unsigned _sp = 0; while (cond) { __builtin_amdgcn_s_sleep(1); \
;     if ((++_sp & 255u) == 0u) { if (xb_ld(&(bar)[XB_TMO])) break; if (_sp > XB_SPIN_CAP) { atomicAdd(&(bar)[XB_TMO], 1u); break; } } } } while (0)
; __device__ __forceinline__ void xcd_barrier(const XcdBarrier& b) {
;     ...
;     if (threadIdx.x == 0) {
;         unsigned* bar = b.bar;
;         __builtin_amdgcn_s_waitcnt(0);
;         unsigned nloc = b.st[0], nx = b.st[1];
;         if (nloc == 0u) { xcd_barrier_complete(bar, b.x, nloc, nx); b.st[0] = nloc; b.st[1] = nx; }
;         const unsigned old = xb_add(&bar[XB_XSUB(b.x)], 1u);
;         const unsigned gen = old / nloc;
;         if (old + 1u == (gen + 1u) * nloc) {
;             __builtin_amdgcn_fence(__ATOMIC_RELEASE, "agent");
;             asm volatile("s_waitcnt vmcnt(0)" ::: "memory");
;             const unsigned og = xb_add(&bar[XB_TOP], 1u);
;             const unsigned tg = og / nx;
;             if (og + 1u == (tg + 1u) * nx) xb_add(&bar[XB_TOPGEN], 1u);
;             else XB_SPIN(xb_ld(&bar[XB_TOPGEN]) == tg, bar);
;             __builtin_amdgcn_fence(__ATOMIC_ACQUIRE, "agent");
;             xb_add(&bar[XB_XGEN(b.x)], 1u);
;             asm volatile("s_waitcnt vmcnt(0)" ::: "memory");
;         } else {
;             XB_SPIN(xb_ld(&bar[XB_XGEN(b.x)]) == gen, bar);
.LBB0_1121:
	v_readlane_b32 s2, v254, 56
	s_lshl_b32 s86, s2, 6
	s_lshl_b64 s[2:3], s[86:87], 2
	s_add_u32 s2, s90, s2
	s_addc_u32 s3, s91, s3
	v_cvt_f32_u32_e32 v0, v3
	global_atomic_add v4, v224, v197, s[2:3] offset:1024 sc0
	v_sub_u32_e32 v5, 0, v3
	v_rcp_iflag_f32_e32 v0, v0
	s_nop 0
	v_mul_f32_e32 v0, 0x4f7ffffe, v0
	v_cvt_u32_f32_e32 v0, v0
	v_mul_lo_u32 v5, v5, v0
	v_mul_hi_u32 v5, v0, v5
	v_add_u32_e32 v0, v0, v5
	s_waitcnt vmcnt(0)
	v_mul_hi_u32 v0, v4, v0
	v_mul_lo_u32 v5, v0, v3
	v_sub_u32_e32 v5, v4, v5
	v_add_u32_e32 v6, 1, v0
	v_cmp_ge_u32_e32 vcc, v5, v3
	v_add_u32_e32 v4, 1, v4
	s_nop 0
	v_cndmask_b32_e32 v0, v0, v6, vcc
	v_sub_u32_e32 v6, v5, v3
	v_cndmask_b32_e32 v5, v5, v6, vcc
	v_add_u32_e32 v6, 1, v0
	v_cmp_ge_u32_e32 vcc, v5, v3
	s_nop 1
	v_cndmask_b32_e32 v0, v0, v6, vcc
	v_mul_lo_u32 v5, v3, v0
	v_add_u32_e32 v3, v5, v3
	v_cmp_ne_u32_e32 vcc, v4, v3
	v_mov_b32_e32 v246, v0
	s_and_saveexec_b64 s[4:5], vcc
	s_xor_b64 s[4:5], exec, s[4:5]
	s_cbranch_execz .LBB0_1134
	s_waitcnt lgkmcnt(0)
	global_load_dword v2, v225, s[2:3] offset:1024 sc1
	s_add_u32 s10, s2, 0x2400
	s_addc_u32 s11, s3, 0
	s_waitcnt vmcnt(0)
	v_cmp_eq_u32_e32 vcc, v2, v0
	s_and_saveexec_b64 s[6:7], vcc
	s_cbranch_execz .LBB0_1133
	s_mov_b32 s22, 1
	s_mov_b64 s[12:13], 0
	s_branch .LBB0_1125

; __device__ __forceinline__ unsigned xb_ld(unsigned* p)              { return __hip_atomic_load(p, __ATOMIC_RELAXED, __HIP_MEMORY_SCOPE_AGENT); }
; __device__ __forceinline__ unsigned xb_add(unsigned* p, unsigned v) { return __hip_atomic_fetch_add(p, v, __ATOMIC_RELAXED, __HIP_MEMORY_SCOPE_AGENT); }
; #define XB_SPIN(cond, bar) do { unsigned _sp = 0; while (cond) { __builtin_amdgcn_s_sleep(1); \
;     if ((++_sp & 255u) == 0u) { if (xb_ld(&(bar)[XB_TMO])) break; if (_sp > XB_SPIN_CAP) { atomicAdd(&(bar)[XB_TMO], 1u); break; } } } } while (0)
; __device__ __forceinline__ void xcd_barrier(const XcdBarrier& b) {
;     ...
;         if (old + 1u == (gen + 1u) * nloc) {
;             __builtin_amdgcn_fence(__ATOMIC_RELEASE, "agent");
;             asm volatile("s_waitcnt vmcnt(0)" ::: "memory");
;             const unsigned og = xb_add(&bar[XB_TOP], 1u);
;             const unsigned tg = og / nx;
;             if (og + 1u == (tg + 1u) * nx) xb_add(&bar[XB_TOPGEN], 1u);
;             else XB_SPIN(xb_ld(&bar[XB_TOPGEN]) == tg, bar);
.LBB0_1134:
	s_andn2_saveexec_b64 s[4:5], s[4:5]
	s_cbranch_execz .LBB0_1150
	buffer_wbl2 sc1
	s_waitcnt lgkmcnt(0)
	s_waitcnt vmcnt(0)
	global_atomic_add v3, v226, v197, s[90:91] offset:1024 sc0
	v_cvt_f32_u32_e32 v0, v2
	v_sub_u32_e32 v4, 0, v2
	s_add_u32 s4, s2, 0x2400
	s_addc_u32 s5, s3, 0
	v_rcp_iflag_f32_e32 v0, v0
	s_mov_b64 s[10:11], -1
	v_mul_f32_e32 v0, 0x4f7ffffe, v0
	v_cvt_u32_f32_e32 v0, v0
	v_mul_lo_u32 v4, v4, v0
	v_mul_hi_u32 v4, v0, v4
	v_add_u32_e32 v0, v0, v4
	s_waitcnt vmcnt(0)
	v_mul_hi_u32 v0, v3, v0
	v_mul_lo_u32 v4, v0, v2
	v_sub_u32_e32 v4, v3, v4
	v_cmp_ge_u32_e32 vcc, v4, v2
	v_add_u32_e32 v5, 1, v0
	v_add_u32_e32 v3, 1, v3
	v_cndmask_b32_e32 v0, v0, v5, vcc
	v_sub_u32_e32 v5, v4, v2
	v_cndmask_b32_e32 v4, v4, v5, vcc
	v_cmp_ge_u32_e32 vcc, v4, v2
	v_add_u32_e32 v4, 1, v0
	s_nop 0
	v_cndmask_b32_e32 v0, v0, v4, vcc
	v_mul_lo_u32 v4, v2, v0
	v_add_u32_e32 v2, v4, v2
	v_cmp_ne_u32_e32 vcc, v3, v2
	v_mov_b64_e32 v[2:3], s[4:5]
	s_and_saveexec_b64 s[6:7], vcc
	s_cbranch_execz .LBB0_1147
	global_load_dword v2, v1, s[4:5] sc1
	s_mov_b64 s[14:15], 0
	s_waitcnt vmcnt(0)
	v_cmp_eq_u32_e32 vcc, v2, v246
	s_and_saveexec_b64 s[12:13], vcc
	s_cbranch_execz .LBB0_1146
	s_add_u32 s10, s90, 0x200
	s_addc_u32 s11, s91, 0
	s_mov_b32 s24, 1
	s_branch .LBB0_1139

; __device__ __forceinline__ unsigned xb_ld(unsigned* p)              { return __hip_atomic_load(p, __ATOMIC_RELAXED, __HIP_MEMORY_SCOPE_AGENT); }
; #define XB_SPIN(cond, bar) do { unsigned _sp = 0; while (cond) { __builtin_amdgcn_s_sleep(1); \
;     if ((++_sp & 255u) == 0u) { if (xb_ld(&(bar)[XB_TMO])) break; if (_sp > XB_SPIN_CAP) { atomicAdd(&(bar)[XB_TMO], 1u); break; } } } } while (0)
; __device__ __forceinline__ void xcd_barrier(const XcdBarrier& b) {
;     ...
;             else XB_SPIN(xb_ld(&bar[XB_TOPGEN]) == tg, bar);
.LBB0_1141:
	global_load_dword v2, v1, s[4:5] sc1
	s_add_i32 s24, s24, 1
	s_mov_b64 s[20:21], -1
	s_waitcnt vmcnt(0)
	v_cmp_ne_u32_e32 vcc, v2, v246
	s_orn2_b64 s[18:19], vcc, exec
	s_branch .LBB0_1138

; __device__ __forceinline__ unsigned xb_add(unsigned* p, unsigned v) { return __hip_atomic_fetch_add(p, v, __ATOMIC_RELAXED, __HIP_MEMORY_SCOPE_AGENT); }
; __device__ __forceinline__ void xcd_barrier(const XcdBarrier& b) {
;     ...
;             if (og + 1u == (tg + 1u) * nx) xb_add(&bar[XB_TOPGEN], 1u);
.LBB0_1147:
	s_or_b64 exec, exec, s[6:7]
	s_and_saveexec_b64 s[4:5], s[10:11]
	s_cbranch_execz .LBB0_1149
	global_atomic_add v225, v197, s[90:91] offset:1024
	global_atomic_add v225, v197, s[90:91] offset:1280
	global_atomic_add v225, v197, s[90:91] offset:1536
	global_atomic_add v225, v197, s[90:91] offset:1792
	global_atomic_add v225, v197, s[90:91] offset:2048
	global_atomic_add v225, v197, s[90:91] offset:2304
	global_atomic_add v225, v197, s[90:91] offset:2560
	global_atomic_add v225, v197, s[90:91] offset:2816
	global_atomic_add v225, v197, s[90:91] offset:3072
	global_atomic_add v225, v197, s[90:91] offset:3328
	global_atomic_add v225, v197, s[90:91] offset:3584
	global_atomic_add v225, v197, s[90:91] offset:3840
	global_atomic_add v226, v197, s[90:91]
	global_atomic_add v226, v197, s[90:91] offset:256
	global_atomic_add v226, v197, s[90:91] offset:512
	global_atomic_add v226, v197, s[90:91] offset:768

; __device__ __forceinline__ unsigned xb_ld(unsigned* p)              { return __hip_atomic_load(p, __ATOMIC_RELAXED, __HIP_MEMORY_SCOPE_AGENT); }
; __device__ __forceinline__ unsigned xb_add(unsigned* p, unsigned v) { return __hip_atomic_fetch_add(p, v, __ATOMIC_RELAXED, __HIP_MEMORY_SCOPE_AGENT); }
; #define XB_SPIN(cond, bar) do { unsigned _sp = 0; while (cond) { __builtin_amdgcn_s_sleep(1); \
;     if ((++_sp & 255u) == 0u) { if (xb_ld(&(bar)[XB_TMO])) break; if (_sp > XB_SPIN_CAP) { atomicAdd(&(bar)[XB_TMO], 1u); break; } } } } while (0)
; __device__ __forceinline__ void xcd_barrier(const XcdBarrier& b) {
;     ...
;         if (old + 1u == (gen + 1u) * nloc) {
;             __builtin_amdgcn_fence(__ATOMIC_RELEASE, "agent");
;             asm volatile("s_waitcnt vmcnt(0)" ::: "memory");
;             const unsigned og = xb_add(&bar[XB_TOP], 1u);
;             const unsigned tg = og / nx;
;             if (og + 1u == (tg + 1u) * nx) xb_add(&bar[XB_TOPGEN], 1u);
;             else XB_SPIN(xb_ld(&bar[XB_TOPGEN]) == tg, bar);
.LBB0_1206:
	buffer_wbl2 sc1
	s_waitcnt lgkmcnt(0)
	s_waitcnt vmcnt(0)
	global_atomic_add v3, v226, v197, s[90:91] offset:1024 sc0
	v_cvt_f32_u32_e32 v0, v2
	v_sub_u32_e32 v4, 0, v2
	s_add_u32 s4, s2, 0x2400
	s_addc_u32 s5, s3, 0
	v_rcp_iflag_f32_e32 v0, v0
	s_mov_b64 s[10:11], -1
	v_mul_f32_e32 v0, 0x4f7ffffe, v0
	v_cvt_u32_f32_e32 v0, v0
	v_mul_lo_u32 v4, v4, v0
	v_mul_hi_u32 v4, v0, v4
	v_add_u32_e32 v0, v0, v4
	s_waitcnt vmcnt(0)
	v_mul_hi_u32 v0, v3, v0
	v_mul_lo_u32 v4, v0, v2
	v_sub_u32_e32 v4, v3, v4
	v_cmp_ge_u32_e32 vcc, v4, v2
	v_add_u32_e32 v5, 1, v0
	v_add_u32_e32 v3, 1, v3
	v_cndmask_b32_e32 v0, v0, v5, vcc
	v_sub_u32_e32 v5, v4, v2
	v_cndmask_b32_e32 v4, v4, v5, vcc
	v_cmp_ge_u32_e32 vcc, v4, v2
	v_add_u32_e32 v4, 1, v0
	s_nop 0
	v_cndmask_b32_e32 v0, v0, v4, vcc
	v_mul_lo_u32 v4, v2, v0
	v_add_u32_e32 v2, v4, v2
	v_cmp_ne_u32_e32 vcc, v3, v2
	v_mov_b64_e32 v[2:3], s[4:5]
	s_and_saveexec_b64 s[6:7], vcc
	s_cbranch_execz .LBB0_1218
	global_load_dword v2, v1, s[4:5] sc1
	s_mov_b64 s[14:15], 0
	s_waitcnt vmcnt(0)
	v_cmp_eq_u32_e32 vcc, v2, v246
	s_and_saveexec_b64 s[12:13], vcc
	s_cbranch_execz .LBB0_1217
	s_add_u32 s10, s90, 0x200
	s_addc_u32 s11, s91, 0
	s_mov_b32 s24, 1
	s_branch .LBB0_1210

; __device__ __forceinline__ unsigned xb_add(unsigned* p, unsigned v) { return __hip_atomic_fetch_add(p, v, __ATOMIC_RELAXED, __HIP_MEMORY_SCOPE_AGENT); }
; __device__ __forceinline__ void xcd_barrier(const XcdBarrier& b) {
;     ...
;             if (og + 1u == (tg + 1u) * nx) xb_add(&bar[XB_TOPGEN], 1u);
.LBB0_1219:
	global_atomic_add v225, v197, s[90:91] offset:1024
	global_atomic_add v225, v197, s[90:91] offset:1280
	global_atomic_add v225, v197, s[90:91] offset:1536
	global_atomic_add v225, v197, s[90:91] offset:1792
	global_atomic_add v225, v197, s[90:91] offset:2048
	global_atomic_add v225, v197, s[90:91] offset:2304
	global_atomic_add v225, v197, s[90:91] offset:2560
	global_atomic_add v225, v197, s[90:91] offset:2816
	global_atomic_add v225, v197, s[90:91] offset:3072
	global_atomic_add v225, v197, s[90:91] offset:3328
	global_atomic_add v225, v197, s[90:91] offset:3584
	global_atomic_add v225, v197, s[90:91] offset:3840
	global_atomic_add v226, v197, s[90:91]
	global_atomic_add v226, v197, s[90:91] offset:256
	global_atomic_add v226, v197, s[90:91] offset:512
	global_atomic_add v226, v197, s[90:91] offset:768
	s_getpc_b64 s[98:99]
